# v75 + P9 row loop waits relaxed (next-row loads overlap compute; single wait before register rotation)
# speedup vs baseline: 1.0040x; 1.0040x over previous
.LBB0_1314:
	s_or_b64 exec, exec, s[2:3]
	s_waitcnt lgkmcnt(0)
	s_barrier
	v_readlane_b32 s3, v233, 20
	v_readfirstlane_b32 s2, v210
	s_ashr_i32 s2, s2, 6
	s_add_i32 s2, s2, s3
	v_readlane_b32 s16, v233, 39
	s_cmpk_gt_i32 s2, 0x3fff
	v_readlane_b32 s30, v233, 53
	v_readlane_b32 s31, v233, 54
	v_readlane_b32 s17, v233, 40
	v_readlane_b32 s18, v233, 41
	v_readlane_b32 s19, v233, 42
	v_readlane_b32 s20, v233, 43
	v_readlane_b32 s21, v233, 44
	v_readlane_b32 s22, v233, 45
	v_readlane_b32 s23, v233, 46
	v_readlane_b32 s24, v233, 47
	v_readlane_b32 s25, v233, 48
	v_readlane_b32 s26, v233, 49
	v_readlane_b32 s27, v233, 50
	v_readlane_b32 s28, v233, 51
	v_readlane_b32 s29, v233, 52
	s_cbranch_scc1 .LBB0_1321
	s_mov_b64 s[14:15], s[30:31]
	v_and_b32_e32 v38, 63, v210
	v_readlane_b32 s16, v233, 2
	v_lshlrev_b32_e32 v32, 4, v38
	v_mov_b32_e32 v33, 0
	v_readlane_b32 s22, v233, 8
	v_readlane_b32 s23, v233, 9
	s_mov_b64 s[4:5], 0x2000
	s_ashr_i32 s3, s2, 31
	v_lshl_add_u64 v[24:25], s[22:23], 0, v[32:33]
	v_lshl_add_u64 v[26:27], v[24:25], 0, s[4:5]
	s_lshl_b64 s[4:5], s[2:3], 12
	s_add_u32 s6, s6, s4
	s_addc_u32 s7, s7, s5
	v_add_co_u32_e32 v34, vcc, 0x3000, v24
	s_add_u32 s4, s12, s4
	s_nop 0
	v_addc_co_u32_e32 v35, vcc, 0, v25, vcc
	s_addc_u32 s5, s13, s5
	s_lshl_b64 s[8:9], s[2:3], 2
	v_add_co_u32_e32 v36, vcc, 0x2000, v24
	s_add_u32 s0, s0, s8
	s_nop 0
	v_addc_co_u32_e32 v37, vcc, 0, v25, vcc
	s_addc_u32 s1, s1, s9
	global_load_dwordx4 v[0:3], v[34:35], off offset:2048
	global_load_dwordx4 v[4:7], v[34:35], off offset:1024
	global_load_dwordx4 v[8:11], v[34:35], off
	global_load_dwordx4 v[12:15], v[26:27], off offset:3072
	global_load_dwordx4 v[16:19], v[26:27], off offset:2048
	global_load_dwordx4 v[20:23], v[26:27], off offset:1024
	s_nop 0
	global_load_dwordx4 v[24:27], v[34:35], off offset:3072
	global_load_dwordx4 v[28:31], v[36:37], off
	v_lshlrev_b32_e32 v68, 3, v38
	global_load_dword v102, v33, s[0:1]
	global_load_dwordx2 v[34:35], v68, s[6:7] nt
	global_load_dwordx2 v[36:37], v68, s[6:7] offset:512 nt
	global_load_dwordx2 v[38:39], v68, s[6:7] offset:1024 nt
	global_load_dwordx2 v[40:41], v68, s[6:7] offset:1536 nt
	global_load_dwordx2 v[56:57], v68, s[4:5] nt
	global_load_dwordx2 v[54:55], v68, s[4:5] offset:512 nt
	global_load_dwordx2 v[52:53], v68, s[4:5] offset:1024 nt
	global_load_dwordx2 v[50:51], v68, s[4:5] offset:1536 nt
	global_load_dwordx2 v[42:43], v68, s[6:7] offset:2048 nt
	global_load_dwordx2 v[44:45], v68, s[6:7] offset:2560 nt
	global_load_dwordx2 v[46:47], v68, s[6:7] offset:3072 nt
	global_load_dwordx2 v[48:49], v68, s[6:7] offset:3584 nt
	global_load_dwordx2 v[60:61], v68, s[4:5] offset:2048 nt
	global_load_dwordx2 v[58:59], v68, s[4:5] offset:2560 nt
	global_load_dwordx2 v[64:65], v68, s[4:5] offset:3072 nt
	global_load_dwordx2 v[62:63], v68, s[4:5] offset:3584 nt
	s_lshl_b64 s[0:1], s[2:3], 13
	s_add_u32 s0, s14, s0
	s_addc_u32 s1, s15, s1
	v_lshl_add_u64 v[66:67], s[0:1], 0, v[32:33]
	s_mov_b64 s[0:1], 0x1000
	v_lshl_add_u64 v[66:67], v[66:67], 0, s[0:1]
	s_add_i32 s0, s2, s96
	s_ashr_i32 s1, s0, 31
	s_ashr_i32 s97, s96, 31
	s_lshl_b64 s[6:7], s[0:1], 12
	s_lshl_b64 s[4:5], s[96:97], 13
	v_or_b32_e32 v68, s6, v68
	v_mov_b32_e32 v69, s7
	s_lshl_b64 s[6:7], s[96:97], 12
	s_lshl_b64 s[0:1], s[0:1], 2
	s_add_u32 s3, s0, 0x30000
	s_addc_u32 s14, s1, 0
	s_lshl_b64 s[8:9], s[96:97], 2
	v_mov_b32_e32 v32, 0x358637bd
	s_mov_b32 s15, 0xf800000
	v_mov_b32_e32 v103, 0x260
	v_readlane_b32 s17, v233, 3
	v_readlane_b32 s18, v233, 4
	v_readlane_b32 s19, v233, 5
	v_readlane_b32 s20, v233, 6
	v_readlane_b32 s21, v233, 7
	v_readlane_b32 s24, v233, 10
	v_readlane_b32 s25, v233, 11
	v_readlane_b32 s26, v233, 12
	v_readlane_b32 s27, v233, 13
	v_readlane_b32 s28, v233, 14
	v_readlane_b32 s29, v233, 15
	v_readlane_b32 s30, v233, 16
	v_readlane_b32 s31, v233, 17
	s_waitcnt vmcnt(0)
	s_branch .LBB0_1317

.LBB0_1319:
	v_fmamk_f32 v105, v102, 0x3a000000, v32
	v_mul_f32_e32 v106, 0x4f800000, v105
	v_cmp_gt_f32_e32 vcc, s15, v105
	v_lshlrev_b32_e32 v112, 16, v57
	v_and_b32_e32 v113, 0xffff0000, v57
	v_cndmask_b32_e32 v105, v105, v106, vcc
	v_sqrt_f32_e32 v106, v105
	s_nop 0
	v_add_u32_e32 v107, -1, v106
	v_fma_f32 v109, -v107, v106, v105
	v_add_u32_e32 v108, 1, v106
	v_cmp_ge_f32_e64 s[0:1], 0, v109
	s_nop 1
	v_cndmask_b32_e64 v107, v106, v107, s[0:1]
	v_fma_f32 v106, -v108, v106, v105
	v_cmp_lt_f32_e64 s[0:1], 0, v106
	s_nop 1
	v_cndmask_b32_e64 v106, v107, v108, s[0:1]
	v_mul_f32_e32 v107, 0x37800000, v106
	v_cndmask_b32_e32 v106, v106, v107, vcc
	v_cmp_class_f32_e32 vcc, v105, v103
	s_nop 1
	v_cndmask_b32_e32 v105, v106, v105, vcc
	v_div_scale_f32 v106, s[0:1], v105, v105, 1.0
	v_rcp_f32_e32 v107, v106
	s_nop 0
	v_fma_f32 v108, -v106, v107, 1.0
	v_fmac_f32_e32 v107, v108, v107
	v_div_scale_f32 v108, vcc, 1.0, v105, 1.0
	v_mul_f32_e32 v109, v108, v107
	v_fma_f32 v110, -v106, v109, v108
	v_fmac_f32_e32 v109, v110, v107
	v_fma_f32 v106, -v106, v109, v108
	v_div_fmas_f32 v106, v106, v107, v109
	v_div_fixup_f32 v110, v106, v105, 1.0
	v_lshlrev_b32_e32 v108, 16, v56
	v_and_b32_e32 v109, 0xffff0000, v56
	v_lshlrev_b32_e32 v106, 16, v34
	v_and_b32_e32 v107, 0xffff0000, v34
	v_pk_mul_f32 v[108:109], v[110:111], v[108:109] op_sel_hi:[0,1]
	v_pk_fma_f32 v[106:107], v[28:29], v[108:109], v[106:107]
	v_lshlrev_b32_e32 v108, 16, v35
	v_and_b32_e32 v109, 0xffff0000, v35
	v_pk_mul_f32 v[112:113], v[110:111], v[112:113] op_sel_hi:[0,1]
	v_pk_fma_f32 v[108:109], v[30:31], v[112:113], v[108:109]
	global_store_dwordx4 v[66:67], v[106:109], off offset:-4096 nt
	v_lshlrev_b32_e32 v112, 16, v55
	v_and_b32_e32 v113, 0xffff0000, v55
	v_lshlrev_b32_e32 v108, 16, v54
	v_and_b32_e32 v109, 0xffff0000, v54
	v_lshlrev_b32_e32 v106, 16, v36
	v_and_b32_e32 v107, 0xffff0000, v36
	v_pk_mul_f32 v[108:109], v[110:111], v[108:109] op_sel_hi:[0,1]
	v_pk_fma_f32 v[106:107], v[20:21], v[108:109], v[106:107]
	v_lshlrev_b32_e32 v108, 16, v37
	v_and_b32_e32 v109, 0xffff0000, v37
	v_pk_mul_f32 v[112:113], v[110:111], v[112:113] op_sel_hi:[0,1]
	v_pk_fma_f32 v[108:109], v[22:23], v[112:113], v[108:109]
	global_store_dwordx4 v[66:67], v[106:109], off offset:-3072 nt
	v_lshlrev_b32_e32 v112, 16, v53
	v_and_b32_e32 v113, 0xffff0000, v53
	v_lshlrev_b32_e32 v108, 16, v52
	v_and_b32_e32 v109, 0xffff0000, v52
	v_lshlrev_b32_e32 v106, 16, v38
	v_and_b32_e32 v107, 0xffff0000, v38
	v_pk_mul_f32 v[108:109], v[110:111], v[108:109] op_sel_hi:[0,1]
	v_pk_fma_f32 v[106:107], v[16:17], v[108:109], v[106:107]
	v_lshlrev_b32_e32 v108, 16, v39
	v_and_b32_e32 v109, 0xffff0000, v39
	v_pk_mul_f32 v[112:113], v[110:111], v[112:113] op_sel_hi:[0,1]
	v_pk_fma_f32 v[108:109], v[18:19], v[112:113], v[108:109]
	global_store_dwordx4 v[66:67], v[106:109], off offset:-2048 nt
	v_lshlrev_b32_e32 v112, 16, v51
	v_and_b32_e32 v113, 0xffff0000, v51
	v_lshlrev_b32_e32 v108, 16, v50
	v_and_b32_e32 v109, 0xffff0000, v50
	v_lshlrev_b32_e32 v106, 16, v40
	v_and_b32_e32 v107, 0xffff0000, v40
	v_pk_mul_f32 v[108:109], v[110:111], v[108:109] op_sel_hi:[0,1]
	v_pk_fma_f32 v[106:107], v[12:13], v[108:109], v[106:107]
	v_lshlrev_b32_e32 v108, 16, v41
	v_and_b32_e32 v109, 0xffff0000, v41
	v_pk_mul_f32 v[112:113], v[110:111], v[112:113] op_sel_hi:[0,1]
	v_pk_fma_f32 v[108:109], v[14:15], v[112:113], v[108:109]
	global_store_dwordx4 v[66:67], v[106:109], off offset:-1024 nt
	v_lshlrev_b32_e32 v112, 16, v61
	v_and_b32_e32 v113, 0xffff0000, v61
	v_lshlrev_b32_e32 v108, 16, v60
	v_and_b32_e32 v109, 0xffff0000, v60
	v_lshlrev_b32_e32 v106, 16, v42
	v_and_b32_e32 v107, 0xffff0000, v42
	v_pk_mul_f32 v[108:109], v[110:111], v[108:109] op_sel_hi:[0,1]
	v_pk_fma_f32 v[106:107], v[8:9], v[108:109], v[106:107]
	v_lshlrev_b32_e32 v108, 16, v43
	v_and_b32_e32 v109, 0xffff0000, v43
	v_pk_mul_f32 v[112:113], v[110:111], v[112:113] op_sel_hi:[0,1]
	v_pk_fma_f32 v[108:109], v[10:11], v[112:113], v[108:109]
	global_store_dwordx4 v[66:67], v[106:109], off nt
	v_lshlrev_b32_e32 v112, 16, v59
	v_and_b32_e32 v113, 0xffff0000, v59
	v_lshlrev_b32_e32 v108, 16, v58
	v_and_b32_e32 v109, 0xffff0000, v58
	v_lshlrev_b32_e32 v106, 16, v44
	v_and_b32_e32 v107, 0xffff0000, v44
	v_pk_mul_f32 v[108:109], v[110:111], v[108:109] op_sel_hi:[0,1]
	v_pk_fma_f32 v[106:107], v[4:5], v[108:109], v[106:107]
	v_lshlrev_b32_e32 v108, 16, v45
	v_and_b32_e32 v109, 0xffff0000, v45
	v_pk_mul_f32 v[112:113], v[110:111], v[112:113] op_sel_hi:[0,1]
	v_pk_fma_f32 v[108:109], v[6:7], v[112:113], v[108:109]
	global_store_dwordx4 v[66:67], v[106:109], off offset:1024 nt
	v_lshlrev_b32_e32 v112, 16, v65
	v_and_b32_e32 v113, 0xffff0000, v65
	v_lshlrev_b32_e32 v108, 16, v64
	v_and_b32_e32 v109, 0xffff0000, v64
	v_lshlrev_b32_e32 v106, 16, v46
	v_and_b32_e32 v107, 0xffff0000, v46
	v_pk_mul_f32 v[108:109], v[110:111], v[108:109] op_sel_hi:[0,1]
	v_pk_fma_f32 v[106:107], v[0:1], v[108:109], v[106:107]
	v_lshlrev_b32_e32 v108, 16, v47
	v_and_b32_e32 v109, 0xffff0000, v47
	v_pk_mul_f32 v[112:113], v[110:111], v[112:113] op_sel_hi:[0,1]
	v_pk_fma_f32 v[108:109], v[2:3], v[112:113], v[108:109]
	global_store_dwordx4 v[66:67], v[106:109], off offset:2048 nt
	v_lshlrev_b32_e32 v112, 16, v63
	v_and_b32_e32 v113, 0xffff0000, v63
	v_lshlrev_b32_e32 v108, 16, v62
	v_and_b32_e32 v109, 0xffff0000, v62
	v_lshlrev_b32_e32 v106, 16, v48
	v_and_b32_e32 v107, 0xffff0000, v48
	v_pk_mul_f32 v[108:109], v[110:111], v[108:109] op_sel_hi:[0,1]
	v_pk_fma_f32 v[106:107], v[24:25], v[108:109], v[106:107]
	v_lshlrev_b32_e32 v108, 16, v49
	v_and_b32_e32 v109, 0xffff0000, v49
	v_pk_mul_f32 v[110:111], v[110:111], v[112:113] op_sel_hi:[0,1]
	v_pk_fma_f32 v[108:109], v[26:27], v[110:111], v[108:109]
	s_andn2_b64 vcc, exec, s[12:13]
	global_store_dwordx4 v[66:67], v[106:109], off offset:3072 nt
	s_cbranch_vccnz .LBB0_1316
	s_waitcnt vmcnt(8)
	v_mov_b64_e32 v[48:49], v[84:85]
	v_mov_b64_e32 v[46:47], v[82:83]
	v_mov_b64_e32 v[44:45], v[80:81]
	v_mov_b64_e32 v[42:43], v[78:79]
	v_mov_b64_e32 v[40:41], v[76:77]
	v_mov_b64_e32 v[38:39], v[74:75]
	v_mov_b64_e32 v[36:37], v[72:73]
	v_mov_b64_e32 v[34:35], v[70:71]
	v_mov_b64_e32 v[62:63], v[100:101]
	v_mov_b64_e32 v[64:65], v[94:95]
	v_mov_b64_e32 v[58:59], v[96:97]
	v_mov_b64_e32 v[60:61], v[98:99]
	v_mov_b64_e32 v[50:51], v[86:87]
	v_mov_b64_e32 v[52:53], v[88:89]
	v_mov_b64_e32 v[54:55], v[90:91]
	v_mov_b64_e32 v[56:57], v[92:93]
	v_mov_b32_e32 v102, v104
	s_branch .LBB0_1316
